# global attention loop: K/V register prefetch distance 2 (plus v029 masked changes)
# baseline (speedup 1.0000x reference)
; template <bool NOMAX> ...
;     ...
;         u32x4 kregB = kreg, vregB = vreg;
;         kreg = *(const u32x4*)(kg + (size_t)ATT_TROW(3) * PITCH); vreg = *(const u32x4*)(vg + (size_t)ATT_TROW(1) * PITCH);
;         int kb2 = 0;
;     ...
;         for (int t = 1; t < NF; t += 2) {
;             ATT_STEP(t, kreg, vreg, kregB, vregB, e0, e1, c0, c1);
;             if (t + 1 < NF) ATT_STEP(t + 1, kregB, vregB, kreg, vreg, c0, c1, e0, e1);
;         }
.LBB0_624:
	s_andn2_b64 vcc, exec, s[0:1]
	s_cbranch_vccnz .LBB0_643
	s_lshl_b32 s0, s93, 6
	s_add_i32 s0, s27, s0
	s_add_i32 s13, s29, -4
	s_add_i32 s14, s0, 0xc0
	s_mov_b32 s6, 3
	s_mov_b32 s15, 0x8000
	s_cmp_gt_i32 s29, 6
	s_cbranch_scc0 .Lg2_p0
	s_sub_i32 s10, s14, 64
	v_mad_i64_i32 v[48:49], s[10:11], s10, v215, v[198:199]
	global_load_dwordx4 v[112:115], v[48:49], off
.Lg2_p0:
	s_cmp_gt_i32 s29, 4
	s_cbranch_scc0 .Lg2_p1
	s_add_i32 s18, s14, 0xffffff40
	v_mad_i64_i32 v[48:49], s[18:19], s18, v215, v[200:201]
	global_load_dwordx4 v[116:119], v[48:49], off
.Lg2_p1:
.LBB0_626:
	s_add_i32 s16, s6, 2
	s_cmp_lt_i32 s16, s29
	s_cselect_b64 s[2:3], -1, 0
	s_cmp_ge_i32 s16, s29
	s_cselect_b64 s[0:1], -1, 0
	s_add_i32 s10, s6, 3
	s_cmp_lt_i32 s10, s29
	s_cselect_b64 s[8:9], -1, 0
	s_cbranch_scc0 .Lg2_w0a
	s_waitcnt vmcnt(2)
	s_branch .Lg2_w1a

.Lg2_w1a:
	s_and_b64 vcc, exec, s[0:1]
	s_cbranch_vccnz .LBB0_628
	v_lshl_add_u32 v48, s12, 13, v220
	ds_write_b128 v48, v[120:123]
.LBB0_628:
	s_add_i32 s7, s15, 0xffffe000
	s_and_b32 s17, s7, 0x2000
	s_add_i32 s7, s35, s17
	v_add_u32_e32 v48, s7, v232
	ds_write_b128 v48, v[124:127] offset:24576
	s_add_i32 s10, s6, 4
	s_cmp_ge_i32 s10, s29
	s_cbranch_scc1 .LBB0_630
	v_mad_i64_i32 v[48:49], s[10:11], s14, v215, v[198:199]
	global_load_dwordx4 v[120:123], v[48:49], off
.LBB0_630:
	s_add_i32 s18, s6, 1
	s_cmp_lt_i32 s18, s29
	s_cselect_b64 s[10:11], -1, 0
	s_andn2_b64 vcc, exec, s[2:3]
	s_cbranch_vccnz .LBB0_632
	s_add_i32 s18, s14, 0xffffff80
	v_mad_i64_i32 v[48:49], s[18:19], s18, v215, v[200:201]
	global_load_dwordx4 v[124:127], v[48:49], off
.LBB0_632:
	s_xor_b32 s17, s17, 0x2000
	v_add_u32_e32 v194, s17, v202
	ds_read_b64_tr_b16 v[184:185], v194 offset:24576
	ds_read_b64_tr_b16 v[186:187], v194 offset:25088
	ds_read_b64_tr_b16 v[180:181], v194 offset:25600
	ds_read_b64_tr_b16 v[182:183], v194 offset:26112
	ds_read_b64_tr_b16 v[176:177], v194 offset:26624
	ds_read_b64_tr_b16 v[178:179], v194 offset:27136
	ds_read_b64_tr_b16 v[164:165], v194 offset:27648
	ds_read_b64_tr_b16 v[166:167], v194 offset:28160
	v_mfma_f32_32x32x16_bf16 v[48:63], v[156:159], v[96:99], 0
	v_add_f32_e32 v80, 0, v32
	v_add_f32_e32 v80, v33, v80
	v_add_f32_e32 v80, v34, v80
	v_add_f32_e32 v156, v35, v80
	v_cvt_pk_bf16_f32 v160, v32, v33
	v_cvt_pk_bf16_f32 v161, v34, v35
	v_mfma_f32_32x32x16_bf16 v[80:95], v[144:147], v[96:99], 0
	v_add_f32_e32 v144, v36, v156
	v_add_f32_e32 v144, v37, v144
	v_add_f32_e32 v144, v38, v144
	v_add_f32_e32 v144, v39, v144
	v_cvt_pk_bf16_f32 v162, v36, v37
	v_cvt_pk_bf16_f32 v163, v38, v39
	v_mfma_f32_32x32x16_bf16 v[48:63], v[152:155], v[100:103], v[48:63]
	v_add_f32_e32 v144, v40, v144
	v_add_f32_e32 v144, v41, v144
	v_add_f32_e32 v144, v42, v144
	v_add_f32_e32 v144, v43, v144
	v_cvt_pk_bf16_f32 v168, v40, v41
	v_cvt_pk_bf16_f32 v169, v42, v43
	v_mfma_f32_32x32x16_bf16 v[80:95], v[136:139], v[100:103], v[80:95]
	v_add_f32_e32 v136, v44, v144
	v_add_f32_e32 v136, v45, v136
	v_add_f32_e32 v136, v46, v136
	v_add_f32_e32 v136, v47, v136
	v_cvt_pk_bf16_f32 v170, v44, v45
	v_cvt_pk_bf16_f32 v171, v46, v47
	v_mfma_f32_32x32x16_bf16 v[48:63], v[148:151], v[104:107], v[48:63]
	v_add_f32_e32 v136, v64, v136
	v_add_f32_e32 v136, v65, v136
	v_add_f32_e32 v136, v66, v136
	v_add_f32_e32 v136, v67, v136
	v_cvt_pk_bf16_f32 v172, v64, v65
	v_cvt_pk_bf16_f32 v173, v66, v67
	v_mfma_f32_32x32x16_bf16 v[80:95], v[132:135], v[104:107], v[80:95]
	v_add_f32_e32 v132, v68, v136
	v_add_f32_e32 v132, v69, v132
	v_add_f32_e32 v132, v70, v132
	v_add_f32_e32 v132, v71, v132
	v_cvt_pk_bf16_f32 v174, v68, v69
	v_cvt_pk_bf16_f32 v175, v70, v71
	v_mfma_f32_32x32x16_bf16 v[48:63], v[140:143], v[108:111], v[48:63]
	v_add_f32_e32 v132, v72, v132
	v_add_f32_e32 v132, v73, v132
	v_add_f32_e32 v132, v74, v132
	v_add_f32_e32 v132, v75, v132
	v_cvt_pk_bf16_f32 v188, v72, v73
	v_cvt_pk_bf16_f32 v189, v74, v75
	v_mfma_f32_32x32x16_bf16 v[80:95], v[128:131], v[108:111], v[80:95]
	v_add_f32_e32 v128, v76, v132
	v_add_f32_e32 v128, v77, v128
	v_add_f32_e32 v128, v78, v128
	v_add_f32_e32 v128, v79, v128
	v_cvt_pk_bf16_f32 v190, v76, v77
	v_cvt_pk_bf16_f32 v191, v78, v79
	s_nop 0
	v_add_f32_e32 v196, v196, v128
	ds_read_b64_tr_b16 v[128:129], v194 offset:28672
	ds_read_b64_tr_b16 v[130:131], v194 offset:29184
	ds_read_b64_tr_b16 v[140:141], v194 offset:29696
	ds_read_b64_tr_b16 v[142:143], v194 offset:30208
	ds_read_b64_tr_b16 v[210:211], v194 offset:30720
	ds_read_b64_tr_b16 v[212:213], v194 offset:31232
	ds_read_b64_tr_b16 v[234:235], v194 offset:31744
	ds_read_b64_tr_b16 v[236:237], v194 offset:32256
	s_waitcnt lgkmcnt(14)
	v_mfma_f32_32x32x16_bf16 v[0:15], v[184:187], v[160:163], v[0:15]
	s_lshl_b32 s17, s12, 13
	s_addk_i32 s17, 0xe000
	s_cmp_lg_u32 s12, 0
	s_cselect_b32 s17, s17, 0x4000
	v_exp_f32_e32 v48, v48
	v_exp_f32_e32 v49, v49
	v_exp_f32_e32 v50, v50
	v_exp_f32_e32 v51, v51
	v_add_u32_e32 v194, s17, v221
	s_waitcnt lgkmcnt(12)
	v_mfma_f32_32x32x16_bf16 v[0:15], v[180:183], v[168:171], v[0:15]
	v_exp_f32_e32 v52, v52
	v_exp_f32_e32 v53, v53
	v_exp_f32_e32 v54, v54
	v_exp_f32_e32 v55, v55
	s_waitcnt lgkmcnt(10)
	v_mfma_f32_32x32x16_bf16 v[0:15], v[176:179], v[172:175], v[0:15]
	v_exp_f32_e32 v56, v56
	v_exp_f32_e32 v57, v57
	v_exp_f32_e32 v58, v58
	v_exp_f32_e32 v59, v59
	ds_read_b128 v[156:159], v194
	ds_read_b128 v[144:147], v194 offset:512
	s_waitcnt lgkmcnt(10)
	v_mfma_f32_32x32x16_bf16 v[0:15], v[164:167], v[188:191], v[0:15]
	v_exp_f32_e32 v60, v60
	v_exp_f32_e32 v61, v61
	v_exp_f32_e32 v62, v62
	v_exp_f32_e32 v63, v63
	ds_read_b128 v[152:155], v194 offset:2048
	ds_read_b128 v[136:139], v194 offset:2560
	s_waitcnt lgkmcnt(10)
	v_mfma_f32_32x32x16_bf16 v[16:31], v[128:131], v[160:163], v[16:31]
	v_exp_f32_e32 v80, v80
	v_exp_f32_e32 v81, v81
	v_exp_f32_e32 v82, v82
	v_exp_f32_e32 v83, v83
	ds_read_b128 v[148:151], v194 offset:4096
	ds_read_b128 v[132:135], v194 offset:4608
	s_waitcnt lgkmcnt(10)
	v_mfma_f32_32x32x16_bf16 v[16:31], v[140:143], v[168:171], v[16:31]
	v_exp_f32_e32 v84, v84
	v_exp_f32_e32 v85, v85
	v_exp_f32_e32 v86, v86
	v_exp_f32_e32 v87, v87
	ds_read_b128 v[140:143], v194 offset:6144
	ds_read_b128 v[128:131], v194 offset:6656
	s_waitcnt lgkmcnt(10)
	v_mfma_f32_32x32x16_bf16 v[16:31], v[210:213], v[172:175], v[16:31]
	v_exp_f32_e32 v88, v88
	v_exp_f32_e32 v89, v89
	v_exp_f32_e32 v90, v90
	v_exp_f32_e32 v91, v91
	s_waitcnt lgkmcnt(8)
	v_mfma_f32_32x32x16_bf16 v[16:31], v[234:237], v[188:191], v[16:31]
	v_exp_f32_e32 v92, v92
	v_exp_f32_e32 v93, v93
	v_exp_f32_e32 v94, v94
	v_exp_f32_e32 v95, v95
	s_add_i32 s17, s12, 1
	s_cmp_lg_u32 s12, 2
	s_cselect_b32 s12, s17, 0
	s_andn2_b64 vcc, exec, s[10:11]
	s_waitcnt lgkmcnt(0)
	s_barrier
	s_cbranch_vccnz .LBB0_640
	s_add_i32 s18, s6, 4
	s_cmp_lt_i32 s18, s29
	s_cbranch_scc0 .Lg2_w0b
	s_waitcnt vmcnt(2)
	s_branch .Lg2_w1b

.Lg2_w1b:
	s_andn2_b64 vcc, exec, s[8:9]
	s_cbranch_vccnz .LBB0_635
	v_lshl_add_u32 v32, s12, 13, v220
	ds_write_b128 v32, v[112:115]
.LBB0_635:
	s_and_b32 s18, s15, 0x2000
	v_add_u32_e32 v32, s18, v222
	ds_write_b128 v32, v[116:119] offset:24576
	s_add_i32 s18, s6, 5
	s_cmp_ge_i32 s18, s29
	s_cbranch_scc1 .LBB0_637
	s_add_i32 s18, s14, 64
	v_mad_i64_i32 v[32:33], s[18:19], s18, v215, v[198:199]
	global_load_dwordx4 v[112:115], v[32:33], off
.LBB0_637:
	s_andn2_b64 vcc, exec, s[8:9]
	s_cbranch_vccnz .LBB0_639
	s_sub_i32 s18, s14, 64
	v_mad_i64_i32 v[32:33], s[18:19], s18, v215, v[200:201]
	global_load_dwordx4 v[116:119], v[32:33], off
